# cache-policy hints: nontemporal stores for the f32 residual stream in the norm phases and nontemporal loads for the read-once f32 weights in weight conversion
# speedup vs baseline: 1.0057x; 1.0052x over previous
.LBB0_346:
	s_mul_i32 s6, s34, 0x244c
	s_mul_i32 s60, s5, 0x244c
	s_mov_b32 s7, s61
	s_mov_b32 s11, s61
	s_mov_b32 s13, s61
	s_mov_b32 s15, s61
	s_mov_b32 s17, s61
	s_mov_b32 s19, s61
	s_mov_b32 s21, s61
	s_mov_b32 s23, s61
	s_mov_b32 s25, s61
	s_mov_b32 s39, s61
	s_mov_b32 s41, s61
	s_mov_b32 s43, s61
	s_mov_b32 s45, s61
	s_mov_b32 s59, s61
	v_lshl_add_u64 v[16:17], s[60:61], 2, v[10:11]
	v_lshl_add_u64 v[18:19], s[6:7], 2, v[10:11]
	s_add_i32 s12, s6, 0x4898
	s_add_i32 s10, s60, 0x4898
	s_add_i32 s16, s6, 0x9130
	s_add_i32 s14, s60, 0x9130
	s_add_i32 s20, s6, 0xd9c8
	s_add_i32 s18, s60, 0xd9c8
	s_add_i32 s24, s6, 0x12260
	s_add_i32 s22, s60, 0x12260
	s_add_i32 s40, s6, 0x16af8
	s_add_i32 s38, s60, 0x16af8
	s_add_i32 s44, s6, 0x1b390
	s_add_i32 s42, s60, 0x1b390
	s_add_i32 s58, s6, 0x1fc28
	s_add_i32 s60, s60, 0x1fc28
	v_lshl_add_u64 v[22:23], s[10:11], 2, v[10:11]
	v_lshl_add_u64 v[24:25], s[12:13], 2, v[10:11]
	v_lshl_add_u64 v[26:27], s[14:15], 2, v[10:11]
	v_lshl_add_u64 v[28:29], s[16:17], 2, v[10:11]
	v_lshl_add_u64 v[30:31], s[18:19], 2, v[10:11]
	v_lshl_add_u64 v[32:33], s[20:21], 2, v[10:11]
	v_lshl_add_u64 v[34:35], s[22:23], 2, v[10:11]
	v_lshl_add_u64 v[36:37], s[24:25], 2, v[10:11]
	v_lshl_add_u64 v[38:39], s[38:39], 2, v[10:11]
	v_lshl_add_u64 v[40:41], s[40:41], 2, v[10:11]
	v_lshl_add_u64 v[42:43], s[42:43], 2, v[10:11]
	v_lshl_add_u64 v[44:45], s[44:45], 2, v[10:11]
	v_lshl_add_u64 v[46:47], s[60:61], 2, v[10:11]
	v_lshl_add_u64 v[48:49], s[58:59], 2, v[10:11]
	flat_load_dword v51, v[18:19] nt
	flat_load_dword v52, v[30:31] nt
	flat_load_dword v53, v[26:27] nt
	flat_load_dword v54, v[22:23] nt
	flat_load_dword v55, v[16:17] nt
	flat_load_dword v56, v[24:25] nt
	flat_load_dword v57, v[28:29] nt
	flat_load_dword v58, v[32:33] nt
	flat_load_dword v59, v[36:37] nt
	flat_load_dword v60, v[46:47] nt
	flat_load_dword v61, v[42:43] nt
	flat_load_dword v62, v[38:39] nt
	flat_load_dword v63, v[34:35] nt
	flat_load_dword v64, v[40:41] nt
	flat_load_dword v65, v[44:45] nt
	flat_load_dword v66, v[48:49] nt
	s_lshl_b32 s36, s34, 1
	s_lshl_b32 s37, s5, 1
	v_or_b32_e32 v0, s36, v3
	v_or_b32_e32 v50, s37, v2
	s_add_i32 s48, s36, 4
	s_add_i32 s50, s37, 4
	s_add_i32 s53, s36, 8
	s_add_i32 s57, s37, 8
	s_add_i32 s62, s36, 12
	s_add_i32 s63, s37, 12
	s_add_i32 s64, s36, 16
	s_add_i32 s65, s37, 16
	s_add_i32 s74, s36, 20
	s_add_i32 s75, s37, 20
	s_add_i32 s76, s36, 24
	s_add_i32 s80, s37, 24
	s_add_i32 s37, s37, 28
	v_mad_u64_u32 v[16:17], s[6:7], v50, s55, v[4:5]
	v_mad_u64_u32 v[18:19], s[6:7], v0, s55, v[4:5]
	s_add_i32 s5, s5, 16
	s_add_i32 s34, s34, 16
	s_add_i32 s35, s35, -16
	s_add_i32 s36, s36, 28
	v_or_b32_e32 v0, s48, v3
	v_or_b32_e32 v17, s50, v2
	v_or_b32_e32 v19, s53, v3
	v_or_b32_e32 v26, s57, v2
	v_or_b32_e32 v32, s62, v3
	v_or_b32_e32 v30, s63, v2
	v_or_b32_e32 v36, s64, v3
	v_or_b32_e32 v34, s65, v2
	v_or_b32_e32 v40, s74, v3
	v_or_b32_e32 v38, s75, v2
	v_or_b32_e32 v44, s76, v3
	v_or_b32_e32 v42, s80, v2
	v_or_b32_e32 v46, s37, v2
	v_or_b32_e32 v48, s36, v3
	s_cmp_lg_u32 s35, 0
	v_mad_u64_u32 v[22:23], s[6:7], v17, s55, v[4:5]
	v_mad_u64_u32 v[24:25], s[6:7], v0, s55, v[4:5]
	v_mad_u64_u32 v[26:27], s[6:7], v26, s55, v[4:5]
	v_mad_u64_u32 v[28:29], s[6:7], v19, s55, v[4:5]
	v_mad_u64_u32 v[30:31], s[6:7], v30, s55, v[4:5]
	v_mad_u64_u32 v[32:33], s[6:7], v32, s55, v[4:5]
	v_mad_u64_u32 v[34:35], s[6:7], v34, s55, v[4:5]
	v_mad_u64_u32 v[36:37], s[6:7], v36, s55, v[4:5]
	v_mad_u64_u32 v[38:39], s[6:7], v38, s55, v[4:5]
	v_mad_u64_u32 v[40:41], s[6:7], v40, s55, v[4:5]
	v_mad_u64_u32 v[42:43], s[6:7], v42, s55, v[4:5]
	v_mad_u64_u32 v[44:45], s[6:7], v44, s55, v[4:5]
	v_mad_u64_u32 v[46:47], s[6:7], v46, s55, v[4:5]
	v_mad_u64_u32 v[48:49], s[6:7], v48, s55, v[4:5]
	s_waitcnt vmcnt(0) lgkmcnt(0)
	v_cndmask_b32_e32 v17, 0, v55, vcc
	v_cndmask_b32_e32 v0, 0, v51, vcc
	v_cndmask_b32_e32 v19, 0, v56, vcc
	v_cndmask_b32_e32 v23, 0, v54, vcc
	v_cndmask_b32_e32 v25, 0, v57, vcc
	v_cndmask_b32_e32 v27, 0, v53, vcc
	v_cndmask_b32_e32 v29, 0, v58, vcc
	v_cndmask_b32_e32 v31, 0, v52, vcc
	v_cndmask_b32_e32 v33, 0, v59, vcc
	v_cndmask_b32_e32 v35, 0, v63, vcc
	v_cndmask_b32_e32 v37, 0, v64, vcc
	v_cndmask_b32_e32 v39, 0, v62, vcc
	v_cndmask_b32_e32 v41, 0, v65, vcc
	v_cndmask_b32_e32 v43, 0, v61, vcc
	v_cndmask_b32_e32 v45, 0, v66, vcc
	v_cndmask_b32_e32 v47, 0, v60, vcc
	ds_write_b32 v16, v17
	ds_write_b32 v18, v0
	ds_write_b32 v22, v23
	ds_write_b32 v24, v19
	ds_write_b32 v26, v27
	ds_write_b32 v28, v25
	ds_write_b32 v30, v31
	ds_write_b32 v32, v29
	ds_write_b32 v34, v35
	ds_write_b32 v36, v33
	ds_write_b32 v38, v39
	ds_write_b32 v40, v37
	ds_write_b32 v42, v43
	ds_write_b32 v44, v41
	ds_write_b32 v46, v47
	ds_write_b32 v48, v45
	s_cbranch_scc1 .LBB0_346
	s_waitcnt lgkmcnt(0)
	ds_read2_b32 v[10:11], v15 offset1:8
	ds_read2_b32 v[24:25], v15 offset0:33 offset1:41
	ds_read2_b32 v[26:27], v15 offset0:66 offset1:74
	ds_read2_b32 v[28:29], v15 offset0:99 offset1:107
	ds_read2_b32 v[30:31], v15 offset0:132 offset1:140
	ds_read2_b32 v[32:33], v15 offset0:165 offset1:173
	s_waitcnt lgkmcnt(5)
	v_bfe_u32 v0, v10, 16, 1
	v_add3_u32 v0, v10, v0, s68
	s_waitcnt lgkmcnt(4)
	v_bfe_u32 v10, v24, 16, 1
	v_lshrrev_b32_e32 v0, 16, v0
	v_add3_u32 v10, v24, v10, s68
	v_and_or_b32 v16, v10, s69, v0
	s_waitcnt lgkmcnt(3)
	v_bfe_u32 v0, v26, 16, 1
	v_add3_u32 v0, v26, v0, s68
	s_waitcnt lgkmcnt(2)
	v_bfe_u32 v10, v28, 16, 1
	ds_read2_b32 v[34:35], v15 offset0:198 offset1:206
	v_lshrrev_b32_e32 v0, 16, v0
	v_add3_u32 v10, v28, v10, s68
	ds_read2_b32 v[36:37], v15 offset0:231 offset1:239
	v_and_or_b32 v17, v10, s69, v0
	s_waitcnt lgkmcnt(3)
	v_bfe_u32 v0, v30, 16, 1
	v_add3_u32 v0, v30, v0, s68
	s_waitcnt lgkmcnt(2)
	v_bfe_u32 v10, v32, 16, 1
	v_lshrrev_b32_e32 v0, 16, v0
	v_add3_u32 v10, v32, v10, s68
	v_and_or_b32 v18, v10, s69, v0
	s_waitcnt lgkmcnt(1)
	v_bfe_u32 v0, v34, 16, 1
	v_add3_u32 v0, v34, v0, s68
	s_waitcnt lgkmcnt(0)
	v_bfe_u32 v10, v36, 16, 1
	v_lshrrev_b32_e32 v0, 16, v0
	v_add3_u32 v10, v36, v10, s68
	v_or_b32_e32 v38, s33, v20
	s_ashr_i32 s5, s4, 31
	v_and_or_b32 v19, v10, s69, v0
	v_ashrrev_i32_e32 v39, 31, v38
	v_bfe_u32 v0, v11, 16, 1
	v_lshl_add_u64 v[22:23], s[4:5], 1, v[6:7]
	v_lshlrev_b64 v[38:39], 12, v[38:39]
	v_add3_u32 v0, v11, v0, s68
	v_bfe_u32 v10, v25, 16, 1
	v_lshl_add_u64 v[38:39], v[22:23], 0, v[38:39]
	v_lshrrev_b32_e32 v0, 16, v0
	v_add3_u32 v10, v25, v10, s68
	flat_store_dwordx4 v[38:39], v[16:19]
	ds_read2_b32 v[24:25], v15 offset0:16 offset1:24
	v_or_b32_e32 v38, s33, v13
	v_and_or_b32 v16, v10, s69, v0
	v_bfe_u32 v0, v27, 16, 1
	v_add3_u32 v0, v27, v0, s68
	v_bfe_u32 v10, v29, 16, 1
	v_lshrrev_b32_e32 v0, 16, v0
	v_add3_u32 v10, v29, v10, s68
	v_and_or_b32 v17, v10, s69, v0
	v_bfe_u32 v0, v31, 16, 1
	v_add3_u32 v0, v31, v0, s68
	v_bfe_u32 v10, v33, 16, 1
	v_lshrrev_b32_e32 v0, 16, v0
	v_add3_u32 v10, v33, v10, s68
	v_and_or_b32 v18, v10, s69, v0
	v_bfe_u32 v0, v35, 16, 1
	v_add3_u32 v0, v35, v0, s68
	v_bfe_u32 v10, v37, 16, 1
	v_lshrrev_b32_e32 v0, 16, v0
	v_add3_u32 v10, v37, v10, s68
	v_and_or_b32 v19, v10, s69, v0
	v_or_b32_e32 v10, s33, v12
	v_ashrrev_i32_e32 v11, 31, v10
	v_lshlrev_b64 v[10:11], 12, v[10:11]
	v_lshl_add_u64 v[10:11], v[22:23], 0, v[10:11]
	flat_store_dwordx4 v[10:11], v[16:19]
	ds_read2_b32 v[10:11], v15 offset0:49 offset1:57
	ds_read2_b32 v[26:27], v15 offset0:82 offset1:90
	ds_read2_b32 v[28:29], v15 offset0:115 offset1:123
	s_waitcnt lgkmcnt(0)
	v_bfe_u32 v0, v24, 16, 1
	v_add3_u32 v0, v24, v0, s68
	v_bfe_u32 v16, v10, 16, 1
	ds_read2_b32 v[30:31], v15 offset0:148 offset1:156
	v_lshrrev_b32_e32 v0, 16, v0
	v_add3_u32 v10, v10, v16, s68
	ds_read2_b32 v[32:33], v15 offset0:181 offset1:189
	v_and_or_b32 v16, v10, s69, v0
	v_bfe_u32 v0, v26, 16, 1
	v_add3_u32 v0, v26, v0, s68
	v_bfe_u32 v10, v28, 16, 1
	ds_read2_b32 v[34:35], v15 offset0:214 offset1:222
	v_lshrrev_b32_e32 v0, 16, v0
	v_add3_u32 v10, v28, v10, s68
	ds_read2_b32 v[36:37], v15 offset0:247 offset1:255
	v_and_or_b32 v17, v10, s69, v0
	s_waitcnt lgkmcnt(0)
	v_bfe_u32 v0, v30, 16, 1
	v_add3_u32 v0, v30, v0, s68
	v_bfe_u32 v10, v32, 16, 1
	v_lshrrev_b32_e32 v0, 16, v0
	v_add3_u32 v10, v32, v10, s68
	v_and_or_b32 v18, v10, s69, v0
	v_bfe_u32 v0, v34, 16, 1
	v_add3_u32 v0, v34, v0, s68
	v_bfe_u32 v10, v36, 16, 1
	v_lshrrev_b32_e32 v0, 16, v0
	v_add3_u32 v10, v36, v10, s68
	v_and_or_b32 v19, v10, s69, v0
	v_ashrrev_i32_e32 v39, 31, v38
	v_bfe_u32 v0, v25, 16, 1
	v_lshlrev_b64 v[38:39], 12, v[38:39]
	v_add3_u32 v0, v25, v0, s68
	v_bfe_u32 v10, v11, 16, 1
	v_lshl_add_u64 v[38:39], v[22:23], 0, v[38:39]
	v_lshrrev_b32_e32 v0, 16, v0
	v_add3_u32 v10, v11, v10, s68
	flat_store_dwordx4 v[38:39], v[16:19]
	s_add_i32 s31, s31, s52
	s_cmpk_lt_i32 s31, 0x1300
	v_and_or_b32 v16, v10, s69, v0
	v_bfe_u32 v0, v27, 16, 1
	v_add3_u32 v0, v27, v0, s68
	v_bfe_u32 v10, v29, 16, 1
	v_lshrrev_b32_e32 v0, 16, v0
	v_add3_u32 v10, v29, v10, s68
	v_and_or_b32 v17, v10, s69, v0
	v_bfe_u32 v0, v31, 16, 1
	v_add3_u32 v0, v31, v0, s68
	v_bfe_u32 v10, v33, 16, 1
	v_lshrrev_b32_e32 v0, 16, v0
	v_add3_u32 v10, v33, v10, s68
	v_and_or_b32 v18, v10, s69, v0
	v_bfe_u32 v0, v35, 16, 1
	v_add3_u32 v0, v35, v0, s68
	v_bfe_u32 v10, v37, 16, 1
	v_lshrrev_b32_e32 v0, 16, v0
	v_add3_u32 v10, v37, v10, s68
	v_and_or_b32 v19, v10, s69, v0
	v_or_b32_e32 v10, s33, v14
	v_ashrrev_i32_e32 v11, 31, v10
	v_lshlrev_b64 v[10:11], 12, v[10:11]
	v_lshl_add_u64 v[10:11], v[22:23], 0, v[10:11]
	flat_store_dwordx4 v[10:11], v[16:19]
	s_waitcnt lgkmcnt(0)
	s_movk_i32 s74, 0x60
	s_movk_i32 s75, 0x7ff
	s_mov_b32 s53, s81
	s_cbranch_scc1 .LBB0_339

.LBB0_353:
	s_or_saveexec_b64 s[12:13], s[10:11]
	s_lshl_b32 s10, s5, 6
	v_or_b32_e32 v0, s10, v20
	s_movk_i32 s5, 0x900
	v_mad_i64_i32 v[2:3], s[18:19], v0, s5, v[16:17]
	s_ashr_i32 s5, s4, 31
	v_lshl_add_u64 v[2:3], s[4:5], 2, v[2:3]
	v_lshlrev_b32_e32 v0, 2, v10
	v_lshl_add_u64 v[18:19], v[2:3], 0, v[0:1]
	v_mov_b32_e32 v6, 0
	v_mov_b32_e32 v7, 0
	v_mov_b32_e32 v8, 0
	v_mov_b32_e32 v9, 0
	v_mov_b32_e32 v2, 0
	v_mov_b32_e32 v3, 0
	v_mov_b32_e32 v4, 0
	v_mov_b32_e32 v5, 0
	s_xor_b64 exec, exec, s[12:13]
	s_cbranch_execz .LBB0_355
	v_add_co_u32_e32 v2, vcc, 0x4000, v18
	s_mov_b32 s5, 0x9000
	s_nop 0
	v_addc_co_u32_e32 v3, vcc, 0, v19, vcc
	v_add_co_u32_e32 v4, vcc, s5, v18
	flat_load_dwordx4 v[26:29], v[18:19] nt
	s_nop 0
	v_addc_co_u32_e32 v5, vcc, 0, v19, vcc
	v_add_co_u32_e32 v6, vcc, 0xd000, v18
	flat_load_dwordx4 v[30:33], v[2:3] offset:2048 nt
	s_nop 0
	flat_load_dwordx4 v[2:5], v[4:5] nt
	v_addc_co_u32_e32 v7, vcc, 0, v19, vcc
	flat_load_dwordx4 v[6:9], v[6:7] offset:2048 nt
	s_waitcnt vmcnt(0) lgkmcnt(0)
	ds_write2_b32 v13, v26, v27 offset1:1
	ds_write2_b32 v13, v28, v29 offset0:2 offset1:3
	ds_write2_b32 v24, v30, v31 offset1:1
	ds_write2_b32 v25, v32, v33 offset1:1

.LBB0_357:
	s_or_saveexec_b64 s[6:7], s[6:7]
	v_mov_b32_e32 v2, 0
	v_mov_b32_e32 v3, 0
	v_mov_b32_e32 v4, 0
	v_mov_b32_e32 v5, 0
	v_mov_b32_e32 v6, 0
	v_mov_b32_e32 v7, 0
	v_mov_b32_e32 v8, 0
	v_mov_b32_e32 v9, 0
	s_xor_b64 exec, exec, s[6:7]
	s_cbranch_execz .LBB0_350
	v_add_co_u32_e32 v2, vcc, 0x12000, v18
	s_mov_b32 s5, 0x1b000
	s_nop 0
	v_addc_co_u32_e32 v3, vcc, 0, v19, vcc
	v_add_co_u32_e32 v4, vcc, 0x16000, v18
	s_nop 1
	v_addc_co_u32_e32 v5, vcc, 0, v19, vcc
	flat_load_dwordx4 v[28:31], v[2:3] nt
	flat_load_dwordx4 v[32:35], v[4:5] offset:2048 nt
	v_add_co_u32_e32 v2, vcc, s5, v18
	s_nop 1
	v_addc_co_u32_e32 v3, vcc, 0, v19, vcc
	v_add_co_u32_e32 v4, vcc, 0x1f000, v18
	s_nop 1
	v_addc_co_u32_e32 v5, vcc, 0, v19, vcc
	flat_load_dwordx4 v[6:9], v[2:3] nt
	s_nop 0
	flat_load_dwordx4 v[2:5], v[4:5] offset:2048 nt
	s_waitcnt vmcnt(0) lgkmcnt(0)
	ds_write2_b32 v0, v28, v29 offset1:1
	ds_write2_b32 v24, v30, v31 offset1:1
	ds_write2_b32 v25, v32, v33 offset1:1
	ds_write2_b32 v26, v34, v35 offset1:1
	s_branch .LBB0_350

.LBB0_364:
	s_or_saveexec_b64 s[12:13], s[10:11]
	s_lshl_b32 s10, s5, 6
	v_or_b32_e32 v0, s10, v20
	s_movk_i32 s5, 0x1200
	v_mad_i64_i32 v[2:3], s[18:19], v0, s5, v[16:17]
	s_ashr_i32 s5, s4, 31
	v_lshl_add_u64 v[2:3], s[4:5], 2, v[2:3]
	v_lshlrev_b32_e32 v0, 2, v10
	v_lshl_add_u64 v[18:19], v[2:3], 0, v[0:1]
	v_mov_b32_e32 v6, 0
	v_mov_b32_e32 v7, 0
	v_mov_b32_e32 v8, 0
	v_mov_b32_e32 v9, 0
	v_mov_b32_e32 v2, 0
	v_mov_b32_e32 v3, 0
	v_mov_b32_e32 v4, 0
	v_mov_b32_e32 v5, 0
	s_xor_b64 exec, exec, s[12:13]
	s_cbranch_execz .LBB0_366
	v_add_co_u32_e32 v2, vcc, 0x9000, v18
	s_mov_b32 s5, 0x12000
	s_nop 0
	v_addc_co_u32_e32 v3, vcc, 0, v19, vcc
	v_add_co_u32_e32 v4, vcc, s5, v18
	flat_load_dwordx4 v[26:29], v[18:19] nt
	s_nop 0
	v_addc_co_u32_e32 v5, vcc, 0, v19, vcc
	v_add_co_u32_e32 v6, vcc, 0x1b000, v18
	flat_load_dwordx4 v[30:33], v[2:3] nt
	s_nop 0
	flat_load_dwordx4 v[2:5], v[4:5] nt
	v_addc_co_u32_e32 v7, vcc, 0, v19, vcc
	flat_load_dwordx4 v[6:9], v[6:7] nt
	s_waitcnt vmcnt(0) lgkmcnt(0)
	ds_write2_b32 v13, v26, v27 offset1:1
	ds_write2_b32 v13, v28, v29 offset0:2 offset1:3
	ds_write2_b32 v24, v30, v31 offset1:1
	ds_write2_b32 v25, v32, v33 offset1:1

.LBB0_368:
	s_or_saveexec_b64 s[6:7], s[6:7]
	v_mov_b32_e32 v2, 0
	v_mov_b32_e32 v3, 0
	v_mov_b32_e32 v4, 0
	v_mov_b32_e32 v5, 0
	v_mov_b32_e32 v6, 0
	v_mov_b32_e32 v7, 0
	v_mov_b32_e32 v8, 0
	v_mov_b32_e32 v9, 0
	s_xor_b64 exec, exec, s[6:7]
	s_cbranch_execz .LBB0_361
	v_add_co_u32_e32 v2, vcc, 0x24000, v18
	s_mov_b32 s5, 0x36000
	s_nop 0
	v_addc_co_u32_e32 v3, vcc, 0, v19, vcc
	v_add_co_u32_e32 v4, vcc, 0x2d000, v18
	s_nop 1
	v_addc_co_u32_e32 v5, vcc, 0, v19, vcc
	flat_load_dwordx4 v[28:31], v[2:3] nt
	flat_load_dwordx4 v[32:35], v[4:5] nt
	v_add_co_u32_e32 v2, vcc, s5, v18
	s_nop 1
	v_addc_co_u32_e32 v3, vcc, 0, v19, vcc
	v_add_co_u32_e32 v4, vcc, 0x3f000, v18
	s_nop 1
	v_addc_co_u32_e32 v5, vcc, 0, v19, vcc
	flat_load_dwordx4 v[6:9], v[2:3] nt
	s_nop 0
	flat_load_dwordx4 v[2:5], v[4:5] nt
	s_waitcnt vmcnt(0) lgkmcnt(0)
	ds_write2_b32 v0, v28, v29 offset1:1
	ds_write2_b32 v24, v30, v31 offset1:1
	ds_write2_b32 v25, v32, v33 offset1:1
	ds_write2_b32 v26, v34, v35 offset1:1
	s_branch .LBB0_361

.LBB0_375:
	s_or_saveexec_b64 s[10:11], s[4:5]
	s_and_b32 s4, s13, 0xffffffc0
	v_or_b32_e32 v2, s4, v20
	v_ashrrev_i32_e32 v3, 31, v2
	v_lshlrev_b64 v[2:3], 13, v[2:3]
	v_lshl_add_u64 v[2:3], v[16:17], 0, v[2:3]
	s_ashr_i32 s13, s12, 31
	v_lshl_add_u64 v[2:3], s[12:13], 2, v[2:3]
	v_lshlrev_b32_e32 v0, 2, v10
	v_lshl_add_u64 v[18:19], v[2:3], 0, v[0:1]
	v_mov_b32_e32 v6, 0
	v_mov_b32_e32 v7, 0
	v_mov_b32_e32 v8, 0
	v_mov_b32_e32 v9, 0
	v_mov_b32_e32 v2, 0
	v_mov_b32_e32 v3, 0
	v_mov_b32_e32 v4, 0
	v_mov_b32_e32 v5, 0
	s_xor_b64 exec, exec, s[10:11]
	s_cbranch_execz .LBB0_377
	v_add_co_u32_e32 v2, vcc, 0x10000, v18
	s_mov_b32 s5, 0x20000
	s_nop 0
	v_addc_co_u32_e32 v3, vcc, 0, v19, vcc
	v_add_co_u32_e32 v4, vcc, s5, v18
	flat_load_dwordx4 v[26:29], v[18:19] nt
	s_nop 0
	v_addc_co_u32_e32 v5, vcc, 0, v19, vcc
	v_add_co_u32_e32 v6, vcc, 0x30000, v18
	flat_load_dwordx4 v[30:33], v[2:3] nt
	s_nop 0
	flat_load_dwordx4 v[2:5], v[4:5] nt
	v_addc_co_u32_e32 v7, vcc, 0, v19, vcc
	flat_load_dwordx4 v[6:9], v[6:7] nt
	s_waitcnt vmcnt(0) lgkmcnt(0)
	ds_write2_b32 v13, v26, v27 offset1:1
	ds_write2_b32 v13, v28, v29 offset0:2 offset1:3
	ds_write2_b32 v24, v30, v31 offset1:1
	ds_write2_b32 v25, v32, v33 offset1:1

.LBB0_379:
	s_or_saveexec_b64 s[6:7], s[6:7]
	v_mov_b32_e32 v2, 0
	v_mov_b32_e32 v3, 0
	v_mov_b32_e32 v4, 0
	v_mov_b32_e32 v5, 0
	v_mov_b32_e32 v6, 0
	v_mov_b32_e32 v7, 0
	v_mov_b32_e32 v8, 0
	v_mov_b32_e32 v9, 0
	s_xor_b64 exec, exec, s[6:7]
	s_cbranch_execz .LBB0_372
	v_add_co_u32_e32 v2, vcc, 0x40000, v18
	s_mov_b32 s5, 0x60000
	s_nop 0
	v_addc_co_u32_e32 v3, vcc, 0, v19, vcc
	v_add_co_u32_e32 v4, vcc, 0x50000, v18
	s_nop 1
	v_addc_co_u32_e32 v5, vcc, 0, v19, vcc
	flat_load_dwordx4 v[28:31], v[2:3] nt
	flat_load_dwordx4 v[32:35], v[4:5] nt
	v_add_co_u32_e32 v2, vcc, s5, v18
	s_nop 1
	v_addc_co_u32_e32 v3, vcc, 0, v19, vcc
	v_add_co_u32_e32 v4, vcc, 0x70000, v18
	s_nop 1
	v_addc_co_u32_e32 v5, vcc, 0, v19, vcc
	flat_load_dwordx4 v[6:9], v[2:3] nt
	s_nop 0
	flat_load_dwordx4 v[2:5], v[4:5] nt
	s_waitcnt vmcnt(0) lgkmcnt(0)
	ds_write2_b32 v0, v28, v29 offset1:1
	ds_write2_b32 v24, v30, v31 offset1:1
	ds_write2_b32 v25, v32, v33 offset1:1
	ds_write2_b32 v26, v34, v35 offset1:1
	s_branch .LBB0_372

.LBB0_386:
	s_or_saveexec_b64 s[10:11], s[4:5]
	s_lshl_b32 s4, s13, 6
	v_or_b32_e32 v2, s4, v20
	v_ashrrev_i32_e32 v3, 31, v2
	v_lshlrev_b64 v[2:3], 11, v[2:3]
	v_lshl_add_u64 v[2:3], v[16:17], 0, v[2:3]
	s_ashr_i32 s13, s12, 31
	v_lshl_add_u64 v[2:3], s[12:13], 2, v[2:3]
	v_lshlrev_b32_e32 v0, 2, v10
	v_lshl_add_u64 v[18:19], v[2:3], 0, v[0:1]
	v_mov_b32_e32 v6, 0
	v_mov_b32_e32 v7, 0
	v_mov_b32_e32 v8, 0
	v_mov_b32_e32 v9, 0
	v_mov_b32_e32 v2, 0
	v_mov_b32_e32 v3, 0
	v_mov_b32_e32 v4, 0
	v_mov_b32_e32 v5, 0
	s_xor_b64 exec, exec, s[10:11]
	s_cbranch_execz .LBB0_388
	v_add_co_u32_e32 v2, vcc, 0x4000, v18
	s_mov_b32 s5, 0x8000
	s_nop 0
	v_addc_co_u32_e32 v3, vcc, 0, v19, vcc
	v_add_co_u32_e32 v4, vcc, s5, v18
	flat_load_dwordx4 v[26:29], v[18:19] nt
	s_nop 0
	v_addc_co_u32_e32 v5, vcc, 0, v19, vcc
	v_add_co_u32_e32 v6, vcc, 0xc000, v18
	flat_load_dwordx4 v[30:33], v[2:3] nt
	s_nop 0
	flat_load_dwordx4 v[2:5], v[4:5] nt
	v_addc_co_u32_e32 v7, vcc, 0, v19, vcc
	flat_load_dwordx4 v[6:9], v[6:7] nt
	s_waitcnt vmcnt(0) lgkmcnt(0)
	ds_write2_b32 v13, v26, v27 offset1:1
	ds_write2_b32 v13, v28, v29 offset0:2 offset1:3
	ds_write2_b32 v24, v30, v31 offset1:1
	ds_write2_b32 v25, v32, v33 offset1:1

.LBB0_390:
	s_or_saveexec_b64 s[6:7], s[6:7]
	v_mov_b32_e32 v2, 0
	v_mov_b32_e32 v3, 0
	v_mov_b32_e32 v4, 0
	v_mov_b32_e32 v5, 0
	v_mov_b32_e32 v6, 0
	v_mov_b32_e32 v7, 0
	v_mov_b32_e32 v8, 0
	v_mov_b32_e32 v9, 0
	s_xor_b64 exec, exec, s[6:7]
	s_cbranch_execz .LBB0_383
	v_add_co_u32_e32 v2, vcc, 0x10000, v18
	s_mov_b32 s5, 0x18000
	s_nop 0
	v_addc_co_u32_e32 v3, vcc, 0, v19, vcc
	v_add_co_u32_e32 v4, vcc, 0x14000, v18
	s_nop 1
	v_addc_co_u32_e32 v5, vcc, 0, v19, vcc
	flat_load_dwordx4 v[28:31], v[2:3] nt
	flat_load_dwordx4 v[32:35], v[4:5] nt
	v_add_co_u32_e32 v2, vcc, s5, v18
	s_nop 1
	v_addc_co_u32_e32 v3, vcc, 0, v19, vcc
	v_add_co_u32_e32 v4, vcc, 0x1c000, v18
	s_nop 1
	v_addc_co_u32_e32 v5, vcc, 0, v19, vcc
	flat_load_dwordx4 v[6:9], v[2:3] nt
	s_nop 0
	flat_load_dwordx4 v[2:5], v[4:5] nt
	s_waitcnt vmcnt(0) lgkmcnt(0)
	ds_write2_b32 v0, v28, v29 offset1:1
	ds_write2_b32 v24, v30, v31 offset1:1
	ds_write2_b32 v25, v32, v33 offset1:1
	ds_write2_b32 v26, v34, v35 offset1:1
	s_branch .LBB0_383

.LBB0_397:
	s_or_saveexec_b64 s[10:11], s[4:5]
	s_lshl_b32 s4, s13, 6
	v_or_b32_e32 v2, s4, v20
	v_ashrrev_i32_e32 v3, 31, v2
	v_lshlrev_b64 v[2:3], 12, v[2:3]
	v_lshl_add_u64 v[2:3], v[16:17], 0, v[2:3]
	s_ashr_i32 s13, s12, 31
	v_lshl_add_u64 v[2:3], s[12:13], 2, v[2:3]
	v_lshlrev_b32_e32 v0, 2, v10
	v_lshl_add_u64 v[18:19], v[2:3], 0, v[0:1]
	v_mov_b32_e32 v6, 0
	v_mov_b32_e32 v7, 0
	v_mov_b32_e32 v8, 0
	v_mov_b32_e32 v9, 0
	v_mov_b32_e32 v2, 0
	v_mov_b32_e32 v3, 0
	v_mov_b32_e32 v4, 0
	v_mov_b32_e32 v5, 0
	s_xor_b64 exec, exec, s[10:11]
	s_cbranch_execz .LBB0_399
	v_add_co_u32_e32 v2, vcc, 0x8000, v18
	flat_load_dwordx4 v[26:29], v[18:19] nt
	s_nop 0
	v_addc_co_u32_e32 v3, vcc, 0, v19, vcc
	v_add_co_u32_e32 v4, vcc, 0x10000, v18
	s_nop 1
	v_addc_co_u32_e32 v5, vcc, 0, v19, vcc
	v_add_co_u32_e32 v6, vcc, 0x18000, v18
	flat_load_dwordx4 v[30:33], v[2:3] nt
	s_nop 0
	flat_load_dwordx4 v[2:5], v[4:5] nt
	v_addc_co_u32_e32 v7, vcc, 0, v19, vcc
	flat_load_dwordx4 v[6:9], v[6:7] nt
	s_waitcnt vmcnt(0) lgkmcnt(0)
	ds_write2_b32 v13, v26, v27 offset1:1
	ds_write2_b32 v13, v28, v29 offset0:2 offset1:3
	ds_write2_b32 v24, v30, v31 offset1:1
	ds_write2_b32 v25, v32, v33 offset1:1

.LBB0_401:
	s_or_saveexec_b64 s[6:7], s[6:7]
	v_mov_b32_e32 v2, 0
	v_mov_b32_e32 v3, 0
	v_mov_b32_e32 v4, 0
	v_mov_b32_e32 v5, 0
	v_mov_b32_e32 v6, 0
	v_mov_b32_e32 v7, 0
	v_mov_b32_e32 v8, 0
	v_mov_b32_e32 v9, 0
	s_xor_b64 exec, exec, s[6:7]
	s_cbranch_execz .LBB0_394
	v_add_co_u32_e32 v2, vcc, 0x20000, v18
	s_mov_b32 s5, 0x30000
	s_nop 0
	v_addc_co_u32_e32 v3, vcc, 0, v19, vcc
	v_add_co_u32_e32 v4, vcc, 0x28000, v18
	s_nop 1
	v_addc_co_u32_e32 v5, vcc, 0, v19, vcc
	flat_load_dwordx4 v[28:31], v[2:3] nt
	flat_load_dwordx4 v[32:35], v[4:5] nt
	v_add_co_u32_e32 v2, vcc, s5, v18
	s_nop 1
	v_addc_co_u32_e32 v3, vcc, 0, v19, vcc
	v_add_co_u32_e32 v4, vcc, 0x38000, v18
	s_nop 1
	v_addc_co_u32_e32 v5, vcc, 0, v19, vcc
	flat_load_dwordx4 v[6:9], v[2:3] nt
	s_nop 0
	flat_load_dwordx4 v[2:5], v[4:5] nt
	s_waitcnt vmcnt(0) lgkmcnt(0)
	ds_write2_b32 v0, v28, v29 offset1:1
	ds_write2_b32 v24, v30, v31 offset1:1
	ds_write2_b32 v25, v32, v33 offset1:1
	ds_write2_b32 v26, v34, v35 offset1:1
	s_branch .LBB0_394

.LBB0_419:
	s_or_saveexec_b64 s[10:11], s[4:5]
	s_lshl_b32 s4, s13, 6
	v_or_b32_e32 v2, s4, v20
	v_ashrrev_i32_e32 v3, 31, v2
	v_lshlrev_b64 v[2:3], 15, v[2:3]
	v_lshl_add_u64 v[2:3], v[16:17], 0, v[2:3]
	s_ashr_i32 s13, s12, 31
	v_lshl_add_u64 v[2:3], s[12:13], 2, v[2:3]
	v_lshlrev_b32_e32 v0, 2, v10
	v_lshl_add_u64 v[18:19], v[2:3], 0, v[0:1]
	v_mov_b32_e32 v6, 0
	v_mov_b32_e32 v7, 0
	v_mov_b32_e32 v8, 0
	v_mov_b32_e32 v9, 0
	v_mov_b32_e32 v2, 0
	v_mov_b32_e32 v3, 0
	v_mov_b32_e32 v4, 0
	v_mov_b32_e32 v5, 0
	s_xor_b64 exec, exec, s[10:11]
	s_cbranch_execz .LBB0_421
	v_add_co_u32_e32 v2, vcc, 0x40000, v18
	s_mov_b32 s5, 0x80000
	s_nop 0
	v_addc_co_u32_e32 v3, vcc, 0, v19, vcc
	v_add_co_u32_e32 v4, vcc, s5, v18
	flat_load_dwordx4 v[26:29], v[18:19] nt
	s_nop 0
	v_addc_co_u32_e32 v5, vcc, 0, v19, vcc
	v_add_co_u32_e32 v6, vcc, 0xc0000, v18
	flat_load_dwordx4 v[30:33], v[2:3] nt
	s_nop 0
	flat_load_dwordx4 v[2:5], v[4:5] nt
	v_addc_co_u32_e32 v7, vcc, 0, v19, vcc
	flat_load_dwordx4 v[6:9], v[6:7] nt
	s_waitcnt vmcnt(0) lgkmcnt(0)
	ds_write2_b32 v13, v26, v27 offset1:1
	ds_write2_b32 v13, v28, v29 offset0:2 offset1:3
	ds_write2_b32 v24, v30, v31 offset1:1
	ds_write2_b32 v25, v32, v33 offset1:1

.LBB0_423:
	s_or_saveexec_b64 s[6:7], s[6:7]
	v_mov_b32_e32 v2, 0
	v_mov_b32_e32 v3, 0
	v_mov_b32_e32 v4, 0
	v_mov_b32_e32 v5, 0
	v_mov_b32_e32 v6, 0
	v_mov_b32_e32 v7, 0
	v_mov_b32_e32 v8, 0
	v_mov_b32_e32 v9, 0
	s_xor_b64 exec, exec, s[6:7]
	s_cbranch_execz .LBB0_416
	v_add_co_u32_e32 v2, vcc, 0x100000, v18
	s_mov_b32 s5, 0x180000
	s_nop 0
	v_addc_co_u32_e32 v3, vcc, 0, v19, vcc
	v_add_co_u32_e32 v4, vcc, 0x140000, v18
	s_nop 1
	v_addc_co_u32_e32 v5, vcc, 0, v19, vcc
	flat_load_dwordx4 v[28:31], v[2:3] nt
	flat_load_dwordx4 v[32:35], v[4:5] nt
	v_add_co_u32_e32 v2, vcc, s5, v18
	s_nop 1
	v_addc_co_u32_e32 v3, vcc, 0, v19, vcc
	v_add_co_u32_e32 v4, vcc, 0x1c0000, v18
	s_nop 1
	v_addc_co_u32_e32 v5, vcc, 0, v19, vcc
	flat_load_dwordx4 v[6:9], v[2:3] nt
	s_nop 0
	flat_load_dwordx4 v[2:5], v[4:5] nt
	s_waitcnt vmcnt(0) lgkmcnt(0)
	ds_write2_b32 v0, v28, v29 offset1:1
	ds_write2_b32 v24, v30, v31 offset1:1
	ds_write2_b32 v25, v32, v33 offset1:1
	ds_write2_b32 v26, v34, v35 offset1:1
	s_branch .LBB0_416

.LBB0_430:
	s_or_saveexec_b64 s[10:11], s[4:5]
	s_and_b32 s4, s13, 0xffffffc0
	v_or_b32_e32 v2, s4, v20
	v_ashrrev_i32_e32 v3, 31, v2
	v_lshlrev_b64 v[2:3], 13, v[2:3]
	v_lshl_add_u64 v[2:3], v[14:15], 0, v[2:3]
	s_ashr_i32 s13, s12, 31
	v_lshl_add_u64 v[2:3], s[12:13], 2, v[2:3]
	v_lshlrev_b32_e32 v0, 2, v10
	v_lshl_add_u64 v[16:17], v[2:3], 0, v[0:1]
	v_mov_b32_e32 v6, 0
	v_mov_b32_e32 v7, 0
	v_mov_b32_e32 v8, 0
	v_mov_b32_e32 v9, 0
	v_mov_b32_e32 v2, 0
	v_mov_b32_e32 v3, 0
	v_mov_b32_e32 v4, 0
	v_mov_b32_e32 v5, 0
	s_xor_b64 exec, exec, s[10:11]
	s_cbranch_execz .LBB0_432
	v_add_co_u32_e32 v2, vcc, 0x10000, v16
	s_mov_b32 s5, 0x20000
	s_nop 0
	v_addc_co_u32_e32 v3, vcc, 0, v17, vcc
	v_add_co_u32_e32 v4, vcc, s5, v16
	flat_load_dwordx4 v[22:25], v[16:17] nt
	s_nop 0
	v_addc_co_u32_e32 v5, vcc, 0, v17, vcc
	v_add_co_u32_e32 v6, vcc, 0x30000, v16
	flat_load_dwordx4 v[26:29], v[2:3] nt
	s_nop 0
	flat_load_dwordx4 v[2:5], v[4:5] nt
	v_addc_co_u32_e32 v7, vcc, 0, v17, vcc
	flat_load_dwordx4 v[6:9], v[6:7] nt
	s_waitcnt vmcnt(0) lgkmcnt(0)
	ds_write2_b32 v11, v22, v23 offset1:1
	ds_write2_b32 v11, v24, v25 offset0:2 offset1:3
	ds_write2_b32 v19, v26, v27 offset1:1
	ds_write2_b32 v21, v28, v29 offset1:1

.LBB0_434:
	s_or_saveexec_b64 s[6:7], s[6:7]
	v_mov_b32_e32 v2, 0
	v_mov_b32_e32 v3, 0
	v_mov_b32_e32 v4, 0
	v_mov_b32_e32 v5, 0
	v_mov_b32_e32 v6, 0
	v_mov_b32_e32 v7, 0
	v_mov_b32_e32 v8, 0
	v_mov_b32_e32 v9, 0
	s_xor_b64 exec, exec, s[6:7]
	s_cbranch_execz .LBB0_427
	v_add_co_u32_e32 v2, vcc, 0x40000, v16
	s_mov_b32 s5, 0x60000
	s_nop 0
	v_addc_co_u32_e32 v3, vcc, 0, v17, vcc
	v_add_co_u32_e32 v4, vcc, 0x50000, v16
	s_nop 1
	v_addc_co_u32_e32 v5, vcc, 0, v17, vcc
	flat_load_dwordx4 v[24:27], v[2:3] nt
	flat_load_dwordx4 v[28:31], v[4:5] nt
	v_add_co_u32_e32 v2, vcc, s5, v16
	s_nop 1
	v_addc_co_u32_e32 v3, vcc, 0, v17, vcc
	v_add_co_u32_e32 v4, vcc, 0x70000, v16
	s_nop 1
	v_addc_co_u32_e32 v5, vcc, 0, v17, vcc
	flat_load_dwordx4 v[6:9], v[2:3] nt
	s_nop 0
	flat_load_dwordx4 v[2:5], v[4:5] nt
	s_waitcnt vmcnt(0) lgkmcnt(0)
	ds_write2_b32 v0, v24, v25 offset1:1
	ds_write2_b32 v19, v26, v27 offset1:1
	ds_write2_b32 v21, v28, v29 offset1:1
	ds_write2_b32 v22, v30, v31 offset1:1
	s_branch .LBB0_427

.LBB0_453:
	v_lshl_add_u64 v[60:61], v[60:61], 0, v[58:59]
	flat_store_dwordx4 v[60:61], v[30:33] nt
	flat_store_dwordx4 v[60:61], v[26:29] offset:1024 nt
	flat_store_dwordx4 v[60:61], v[22:25] offset:2048 nt
	flat_store_dwordx4 v[60:61], v[18:21] offset:3072 nt
	v_add_co_u32_e32 v60, vcc, 0x1000, v60
	s_nop 1
	v_addc_co_u32_e32 v61, vcc, 0, v61, vcc
	flat_store_dwordx4 v[60:61], v[14:17] nt
	flat_store_dwordx4 v[60:61], v[10:13] offset:1024 nt
	flat_store_dwordx4 v[60:61], v[6:9] offset:2048 nt
	flat_store_dwordx4 v[60:61], v[2:5] offset:3072 nt
	s_or_b64 exec, exec, s[8:9]
	s_and_saveexec_b64 s[10:11], s[6:7]
	s_cbranch_execz .LBB0_448
